# packed vs scalar fp32 beside MFMAs: the 32 packed f32 ops of the prompt-attention tile loop split into single f32 ops
# baseline (speedup 1.0000x reference)
; __device__ __forceinline__ int crow(int r, int hi) { return (r & 3) + 8 * (r >> 2) + 4 * hi; }
; __device__ __forceinline__ void fox_prompt_unit(const Params& p, int b, int h, int qb, unsigned char* lds) {
;     ...
;             for (int g = 0; g < 4; ++g) {
;                 const f32x4 c0 = *(const f32x4*)(sBc + 8 * g + 4 * hi);
;                 const f32x4 c1 = *(const f32x4*)(sBc + 32 + 8 * g + 4 * hi);
; #pragma unroll
;                 for (int e = 0; e < 4; ++e) {
;                     s0[4 * g + e] = fmaf(s0[4 * g + e], 0.125f * LOG2E, c0[e]);
;                     s1[4 * g + e] = fmaf(s1[4 * g + e], 0.125f * LOG2E, c1[e]);
;                 }
;             }
;             if (needmask) {
;                 asm volatile("; causal mask" ::: "memory");
; #pragma unroll
;                 for (int r = 0; r < 16; ++r) { const int kk = key0 + crow(r, hi); if (kk > myq) s0[r] = -INFINITY; if (kk + 32 > myq || !two) s1[r] = -INFINITY; }
;             }
.LBB0_936:
	v_lshl_add_u32 v0, s5, 8, v109
	ds_read_b128 v[114:117], v0 offset:18944
	ds_read_b128 v[118:121], v0 offset:18976
	ds_read_b128 v[122:125], v0 offset:19008
	ds_read_b128 v[126:129], v0 offset:19040
	ds_read_b128 v[130:133], v0 offset:19072
	ds_read_b128 v[134:137], v0 offset:19104
	ds_read_b128 v[138:141], v0 offset:19136
	ds_read_b128 v[142:145], v0 offset:19168
	s_add_i32 s13, s4, 63
	s_waitcnt lgkmcnt(4)
	v_fma_f32 v64, v64, s54, v128
	v_fma_f32 v65, v65, s54, v129
	v_fma_f32 v60, v60, s54, v124
	v_fma_f32 v61, v61, s54, v125
	v_fma_f32 v56, v56, s54, v120
	v_fma_f32 v57, v57, s54, v121
	v_fma_f32 v100, v52, s54, v116
	v_fma_f32 v101, v53, s54, v117
	v_fma_f32 v52, v62, s54, v126
	v_fma_f32 v53, v63, s54, v127
	v_fma_f32 v58, v58, s54, v122
	v_fma_f32 v59, v59, s54, v123
	v_fma_f32 v54, v54, s54, v118
	v_fma_f32 v55, v55, s54, v119
	v_fma_f32 v50, v50, s54, v114
	v_fma_f32 v51, v51, s54, v115
	s_waitcnt lgkmcnt(0)
	v_fma_f32 v48, v48, s54, v144
	v_fma_f32 v49, v49, s54, v145
	v_fma_f32 v44, v44, s54, v140
	v_fma_f32 v45, v45, s54, v141
	v_fma_f32 v40, v40, s54, v136
	v_fma_f32 v41, v41, s54, v137
	v_fma_f32 v62, v36, s54, v132
	v_fma_f32 v63, v37, s54, v133
	v_fma_f32 v36, v46, s54, v142
	v_fma_f32 v37, v47, s54, v143
	v_fma_f32 v42, v42, s54, v138
	v_fma_f32 v43, v43, s54, v139
	v_fma_f32 v38, v38, s54, v134
	v_fma_f32 v39, v39, s54, v135
	s_cmp_le_i32 s13, s10
	v_fma_f32 v34, v34, s54, v130
	v_fma_f32 v35, v35, s54, v131
	s_cbranch_scc1 .LBB0_938
	v_add_u32_e32 v0, s4, v105
	v_add_u32_e32 v46, 32, v0
	v_cmp_le_i32_e32 vcc, v46, v94
	s_and_b64 vcc, s[6:7], vcc
	v_add_u32_e32 v46, 33, v0
	v_cndmask_b32_e32 v34, v204, v34, vcc
	v_cmp_lt_i32_e32 vcc, v0, v94
	s_nop 1
	v_cndmask_b32_e32 v51, v204, v51, vcc
	v_cmp_le_i32_e32 vcc, v0, v94
	s_nop 1
	v_cndmask_b32_e32 v50, v204, v50, vcc
	v_cmp_le_i32_e32 vcc, v46, v94
	s_and_b64 vcc, s[6:7], vcc
	v_add_u32_e32 v46, 2, v0
	v_cndmask_b32_e32 v35, v204, v35, vcc
	v_cmp_le_i32_e32 vcc, v46, v94
	v_add_u32_e32 v46, 34, v0
	s_nop 0
	v_cndmask_b32_e32 v100, v204, v100, vcc
	v_cmp_le_i32_e32 vcc, v46, v94
	s_and_b64 vcc, s[6:7], vcc
	v_add_u32_e32 v46, 3, v0
	v_cndmask_b32_e32 v62, v204, v62, vcc
	v_cmp_le_i32_e32 vcc, v46, v94
	v_add_u32_e32 v46, 35, v0
	s_nop 0
	v_cndmask_b32_e32 v101, v204, v101, vcc
	v_cmp_le_i32_e32 vcc, v46, v94
	s_and_b64 vcc, s[6:7], vcc
	v_add_u32_e32 v46, 8, v0
	v_cndmask_b32_e32 v63, v204, v63, vcc
	v_cmp_le_i32_e32 vcc, v46, v94
	v_add_u32_e32 v46, 40, v0
	s_nop 0
	v_cndmask_b32_e32 v54, v204, v54, vcc
	v_cmp_le_i32_e32 vcc, v46, v94
	s_and_b64 vcc, s[6:7], vcc
	v_add_u32_e32 v46, 9, v0
	v_cndmask_b32_e32 v38, v204, v38, vcc
	v_cmp_le_i32_e32 vcc, v46, v94
	v_add_u32_e32 v46, 41, v0
	s_nop 0
	v_cndmask_b32_e32 v55, v204, v55, vcc
	v_cmp_le_i32_e32 vcc, v46, v94
	s_and_b64 vcc, s[6:7], vcc
	v_add_u32_e32 v46, 10, v0
	v_cndmask_b32_e32 v39, v204, v39, vcc
	v_cmp_le_i32_e32 vcc, v46, v94
	v_add_u32_e32 v46, 42, v0
	s_nop 0
	v_cndmask_b32_e32 v56, v204, v56, vcc
	v_cmp_le_i32_e32 vcc, v46, v94
	s_and_b64 vcc, s[6:7], vcc
	v_add_u32_e32 v46, 11, v0
	v_cndmask_b32_e32 v40, v204, v40, vcc
	v_cmp_le_i32_e32 vcc, v46, v94
	v_add_u32_e32 v46, 43, v0
	s_nop 0
	v_cndmask_b32_e32 v57, v204, v57, vcc
	v_cmp_le_i32_e32 vcc, v46, v94
	s_and_b64 vcc, s[6:7], vcc
	v_add_u32_e32 v46, 16, v0
	v_cndmask_b32_e32 v41, v204, v41, vcc
	v_cmp_le_i32_e32 vcc, v46, v94
	v_add_u32_e32 v46, 48, v0
	s_nop 0
	v_cndmask_b32_e32 v58, v204, v58, vcc
	v_cmp_le_i32_e32 vcc, v46, v94
	s_and_b64 vcc, s[6:7], vcc
	v_add_u32_e32 v46, 17, v0
	v_cndmask_b32_e32 v42, v204, v42, vcc
	v_cmp_le_i32_e32 vcc, v46, v94
	v_add_u32_e32 v46, 49, v0
	s_nop 0
	v_cndmask_b32_e32 v59, v204, v59, vcc
	v_cmp_le_i32_e32 vcc, v46, v94
	s_and_b64 vcc, s[6:7], vcc
	v_add_u32_e32 v46, 18, v0
	v_cndmask_b32_e32 v43, v204, v43, vcc
	v_cmp_le_i32_e32 vcc, v46, v94
	v_add_u32_e32 v46, 50, v0
	s_nop 0
	v_cndmask_b32_e32 v60, v204, v60, vcc
	v_cmp_le_i32_e32 vcc, v46, v94
	s_and_b64 vcc, s[6:7], vcc
	v_add_u32_e32 v46, 19, v0
	v_cndmask_b32_e32 v44, v204, v44, vcc
	v_cmp_le_i32_e32 vcc, v46, v94
	v_add_u32_e32 v46, 51, v0
	s_nop 0
	v_cndmask_b32_e32 v61, v204, v61, vcc
	v_cmp_le_i32_e32 vcc, v46, v94
	s_and_b64 vcc, s[6:7], vcc
	v_add_u32_e32 v46, 24, v0
	v_cndmask_b32_e32 v45, v204, v45, vcc
	v_cmp_le_i32_e32 vcc, v46, v94
	v_add_u32_e32 v46, 56, v0
	s_nop 0
	v_cndmask_b32_e32 v52, v204, v52, vcc
	v_cmp_le_i32_e32 vcc, v46, v94
	s_and_b64 vcc, s[6:7], vcc
	v_add_u32_e32 v46, 25, v0
	v_cndmask_b32_e32 v36, v204, v36, vcc
	v_cmp_le_i32_e32 vcc, v46, v94
	v_add_u32_e32 v46, 57, v0
	s_nop 0
	v_cndmask_b32_e32 v53, v204, v53, vcc
	v_cmp_le_i32_e32 vcc, v46, v94
	s_and_b64 vcc, s[6:7], vcc
	v_add_u32_e32 v46, 26, v0
	v_cndmask_b32_e32 v37, v204, v37, vcc
	v_cmp_le_i32_e32 vcc, v46, v94
	v_add_u32_e32 v46, 58, v0
	s_nop 0
	v_cndmask_b32_e32 v64, v204, v64, vcc
	v_cmp_le_i32_e32 vcc, v46, v94
	s_and_b64 vcc, s[6:7], vcc
	v_add_u32_e32 v46, 27, v0
	v_cndmask_b32_e32 v48, v204, v48, vcc
	v_cmp_le_i32_e32 vcc, v46, v94
	v_add_u32_e32 v0, 59, v0
	s_nop 0
	v_cndmask_b32_e32 v65, v204, v65, vcc
	v_cmp_le_i32_e32 vcc, v0, v94
	s_and_b64 vcc, s[6:7], vcc
	s_nop 0
	v_cndmask_b32_e32 v49, v204, v49, vcc
; __device__ __forceinline__ unsigned pk2(float lo, float hi) { f32x2v v = {lo, hi}; hwbf16x2 b = __builtin_convertvector(v, hwbf16x2); return __builtin_bit_cast(unsigned, b); }
; __device__ __forceinline__ void fox_prompt_unit(const Params& p, int b, int h, int qb, unsigned char* lds) {
;     ...
;             float mx = -INFINITY;
; #pragma unroll
;             for (int r = 0; r < 16; ++r) mx = fmaxf(mx, fmaxf(s0[r], s1[r]));
;             mx = fmaxf(mx, shx(mx, 32, lane));
;             const float mnew = fmaxf(mrun, mx);
;             const float alpha = __builtin_amdgcn_exp2f(mrun - mnew);
;             mrun = mnew;
;             float ps = 0.f;
; #pragma unroll
;             for (int r = 0; r < 16; ++r) { s0[r] = __builtin_amdgcn_exp2f(s0[r] - mnew); s1[r] = __builtin_amdgcn_exp2f(s1[r] - mnew); ps += s0[r] + s1[r]; }
;             lrun = lrun * alpha + ps;
; #pragma unroll
;             for (int r = 0; r < 16; ++r) { o0[r] *= alpha; o1[r] *= alpha; }
; #pragma unroll
;             for (int kb = 0; kb < 2; ++kb) {
;                 if (kb == 1 && !two) break;
; #pragma unroll
;                 for (int s = 0; s < 2; ++s) {
;                     u32x4 pw;
;                     if (kb == 0) { pw.x = pk2(s0[8 * s + 0], s0[8 * s + 1]); pw.y = pk2(s0[8 * s + 2], s0[8 * s + 3]); pw.z = pk2(s0[8 * s + 4], s0[8 * s + 5]); pw.w = pk2(s0[8 * s + 6], s0[8 * s + 7]); }
;                     else         { pw.x = pk2(s1[8 * s + 0], s1[8 * s + 1]); pw.y = pk2(s1[8 * s + 2], s1[8 * s + 3]); pw.z = pk2(s1[8 * s + 4], s1[8 * s + 5]); pw.w = pk2(s1[8 * s + 6], s1[8 * s + 7]); }
;                     const bf16x8 pf = __builtin_bit_cast(bf16x8, pw);
;                     const int kofs = 32 * kb + 16 * s + 4 * hi;
; #pragma unroll
;                     for (int db = 0; db < 2; ++db) {
;                         const bf16_t* vp = Vc + (db * 32 + r32) * 72 + kofs;
;                         const u32x2 lo = *(const u32x2*)vp, hi2 = *(const u32x2*)(vp + 8);
;                         const bf16x8 vf = __builtin_bit_cast(bf16x8, (u32x4){lo.x, lo.y, hi2.x, hi2.y});
;                         if (db == 0) o0 = __builtin_amdgcn_mfma_f32_32x32x16_bf16(vf, pf, o0, 0, 0, 0);
;                         else         o1 = __builtin_amdgcn_mfma_f32_32x32x16_bf16(vf, pf, o1, 0, 0, 0);
;                     }
;                 }
;             }
.LBB0_938:
	v_max_f32_e32 v0, v34, v34
	v_max_f32_e32 v46, v50, v50
	v_max_f32_e32 v0, v46, v0
	v_max_f32_e32 v46, v35, v35
	v_max_f32_e32 v47, v51, v51
	v_max_f32_e32 v46, v47, v46
	s_mov_b32 s13, 0xff800000
	v_max3_f32 v0, v0, s13, v46
	v_max_f32_e32 v46, v62, v62
	v_max_f32_e32 v47, v100, v100
	v_max_f32_e32 v46, v47, v46
	v_max_f32_e32 v47, v63, v63
	v_max_f32_e32 v113, v101, v101
	v_max_f32_e32 v47, v113, v47
	v_max3_f32 v0, v0, v46, v47
	v_max_f32_e32 v46, v38, v38
	v_max_f32_e32 v47, v54, v54
	v_max_f32_e32 v46, v47, v46
	v_max_f32_e32 v47, v39, v39
	v_max_f32_e32 v113, v55, v55
	v_max_f32_e32 v47, v113, v47
	v_max3_f32 v0, v0, v46, v47
	v_max_f32_e32 v46, v40, v40
	v_max_f32_e32 v47, v56, v56
	v_max_f32_e32 v46, v47, v46
	v_max_f32_e32 v47, v41, v41
	v_max_f32_e32 v113, v57, v57
	v_max_f32_e32 v47, v113, v47
	v_max3_f32 v0, v0, v46, v47
	v_max_f32_e32 v46, v42, v42
	v_max_f32_e32 v47, v58, v58
	v_max_f32_e32 v46, v47, v46
	v_max_f32_e32 v47, v43, v43
	v_max_f32_e32 v113, v59, v59
	v_max_f32_e32 v47, v113, v47
	v_max3_f32 v0, v0, v46, v47
	v_max_f32_e32 v46, v44, v44
	v_max_f32_e32 v47, v60, v60
	v_max_f32_e32 v46, v47, v46
	v_max_f32_e32 v47, v45, v45
	v_max_f32_e32 v113, v61, v61
	v_max_f32_e32 v47, v113, v47
	v_max3_f32 v0, v0, v46, v47
	v_max_f32_e32 v46, v36, v36
	v_max_f32_e32 v47, v52, v52
	v_max_f32_e32 v46, v47, v46
	v_max_f32_e32 v47, v37, v37
	v_max_f32_e32 v113, v53, v53
	v_max_f32_e32 v47, v113, v47
	v_max3_f32 v0, v0, v46, v47
	v_max_f32_e32 v46, v48, v48
	v_max_f32_e32 v47, v64, v64
	v_max_f32_e32 v46, v47, v46
	v_max_f32_e32 v47, v49, v49
	v_max_f32_e32 v113, v65, v65
	v_max_f32_e32 v47, v113, v47
	v_max3_f32 v0, v0, v46, v47
	ds_bpermute_b32 v46, v107, v0
	s_mulk_i32 s5, 0x2500
	s_andn2_b64 vcc, exec, s[6:7]
	s_waitcnt lgkmcnt(0)
	v_max3_f32 v46, v112, v0, v46
	v_sub_f32_e32 v47, v50, v46
	v_sub_f32_e32 v50, v51, v46
	v_sub_f32_e32 v51, v100, v46
	v_sub_f32_e32 v100, v101, v46
	v_add_u32_e32 v101, s5, v110
	v_sub_f32_e32 v0, v112, v46
	v_add_u32_e32 v112, 0x1000, v101
	ds_read2_b64 v[114:117], v101 offset1:2
	ds_read2_b64 v[122:125], v112 offset0:64 offset1:66
	v_sub_f32_e32 v54, v54, v46
	v_sub_f32_e32 v55, v55, v46
	v_sub_f32_e32 v56, v56, v46
	v_sub_f32_e32 v57, v57, v46
	v_exp_f32_e32 v47, v47
	v_exp_f32_e32 v50, v50
	v_exp_f32_e32 v51, v51
	v_exp_f32_e32 v100, v100
	v_exp_f32_e32 v54, v54
	v_exp_f32_e32 v55, v55
	v_exp_f32_e32 v56, v56
	v_exp_f32_e32 v57, v57
	v_exp_f32_e32 v0, v0
	v_cvt_pk_bf16_f32 v118, v47, v50
	v_cvt_pk_bf16_f32 v119, v51, v100
	v_cvt_pk_bf16_f32 v120, v54, v55
	v_mul_f32_e32 v32, v32, v0
	v_mul_f32_e32 v33, v33, v0
	v_mul_f32_e32 v30, v30, v0
	v_mul_f32_e32 v31, v31, v0
	v_mul_f32_e32 v28, v28, v0
	v_mul_f32_e32 v29, v29, v0
	v_mul_f32_e32 v26, v26, v0
	v_mul_f32_e32 v27, v27, v0
	v_mul_f32_e32 v24, v24, v0
	v_mul_f32_e32 v25, v25, v0
	v_mul_f32_e32 v22, v22, v0
	v_mul_f32_e32 v23, v23, v0
	v_mul_f32_e32 v20, v20, v0
	v_mul_f32_e32 v21, v21, v0
	v_mul_f32_e32 v18, v18, v0
	v_mul_f32_e32 v19, v19, v0
	v_mul_f32_e32 v16, v16, v0
	v_mul_f32_e32 v17, v17, v0
	v_mul_f32_e32 v14, v14, v0
	v_mul_f32_e32 v15, v15, v0
	v_cvt_pk_bf16_f32 v121, v56, v57
	v_mul_f32_e32 v12, v12, v0
	v_mul_f32_e32 v13, v13, v0
	v_mul_f32_e32 v10, v10, v0
	v_mul_f32_e32 v11, v11, v0
	v_mul_f32_e32 v8, v8, v0
	v_mul_f32_e32 v9, v9, v0
	v_mul_f32_e32 v6, v6, v0
	v_mul_f32_e32 v7, v7, v0
	v_mul_f32_e32 v4, v4, v0
	v_mul_f32_e32 v5, v5, v0
	v_mul_f32_e32 v2, v2, v0
	v_mul_f32_e32 v3, v3, v0
	s_waitcnt lgkmcnt(1)
	v_mfma_f32_32x32x16_bf16 v[18:33], v[114:117], v[118:121], v[18:33]
	ds_read2_b64 v[114:117], v101 offset0:4 offset1:6
	v_sub_f32_e32 v58, v58, v46
	v_sub_f32_e32 v59, v59, v46
	v_sub_f32_e32 v60, v60, v46
	v_sub_f32_e32 v61, v61, v46
	v_sub_f32_e32 v52, v52, v46
	v_sub_f32_e32 v53, v53, v46
	s_waitcnt lgkmcnt(1)
	v_mfma_f32_32x32x16_bf16 v[2:17], v[122:125], v[118:121], v[2:17]
	ds_read2_b64 v[122:125], v112 offset0:68 offset1:70
	v_sub_f32_e32 v64, v64, v46
	v_sub_f32_e32 v65, v65, v46
	v_exp_f32_e32 v58, v58
	v_exp_f32_e32 v59, v59
	v_exp_f32_e32 v60, v60
	v_exp_f32_e32 v61, v61
	v_exp_f32_e32 v52, v52
	v_exp_f32_e32 v53, v53
	v_exp_f32_e32 v64, v64
	v_exp_f32_e32 v65, v65
	v_cvt_pk_bf16_f32 v118, v58, v59
	v_cvt_pk_bf16_f32 v119, v60, v61
	v_cvt_pk_bf16_f32 v120, v52, v53
	v_cvt_pk_bf16_f32 v121, v64, v65
	v_sub_f32_e32 v34, v34, v46
	v_sub_f32_e32 v35, v35, v46
	s_waitcnt lgkmcnt(1)
	v_mfma_f32_32x32x16_bf16 v[18:33], v[114:117], v[118:121], v[18:33]
	v_sub_f32_e32 v62, v62, v46
	v_sub_f32_e32 v63, v63, v46
	v_sub_f32_e32 v38, v38, v46
	v_sub_f32_e32 v39, v39, v46
	v_sub_f32_e32 v40, v40, v46
	v_sub_f32_e32 v41, v41, v46
	v_sub_f32_e32 v42, v42, v46
	s_waitcnt lgkmcnt(0)
	v_mfma_f32_32x32x16_bf16 v[2:17], v[122:125], v[118:121], v[2:17]
	v_sub_f32_e32 v43, v43, v46
	v_sub_f32_e32 v44, v44, v46
	v_sub_f32_e32 v45, v45, v46
	v_sub_f32_e32 v36, v36, v46
	v_sub_f32_e32 v37, v37, v46
	v_sub_f32_e32 v48, v48, v46
	v_sub_f32_e32 v49, v49, v46
	v_exp_f32_e32 v34, v34
	v_exp_f32_e32 v35, v35
	v_exp_f32_e32 v62, v62
	v_exp_f32_e32 v63, v63
	v_exp_f32_e32 v38, v38
	v_exp_f32_e32 v39, v39
	v_exp_f32_e32 v40, v40
	v_exp_f32_e32 v41, v41
	v_exp_f32_e32 v42, v42
	v_exp_f32_e32 v43, v43
	v_exp_f32_e32 v44, v44
	v_exp_f32_e32 v45, v45
	v_exp_f32_e32 v36, v36
	v_exp_f32_e32 v37, v37
	v_exp_f32_e32 v48, v48
	v_exp_f32_e32 v49, v49
	s_cbranch_vccnz .LBB0_940
	ds_read2_b64 v[114:117], v101 offset0:8 offset1:10
	v_cvt_pk_bf16_f32 v118, v34, v35
	v_cvt_pk_bf16_f32 v119, v62, v63
	v_cvt_pk_bf16_f32 v120, v38, v39
	v_cvt_pk_bf16_f32 v121, v40, v41
	s_waitcnt lgkmcnt(0)
	s_nop 0
	v_mfma_f32_32x32x16_bf16 v[18:33], v[114:117], v[118:121], v[18:33]
	ds_read2_b64 v[114:117], v112 offset0:72 offset1:74
	s_waitcnt lgkmcnt(0)
	v_mfma_f32_32x32x16_bf16 v[2:17], v[114:117], v[118:121], v[2:17]
	ds_read2_b64 v[114:117], v101 offset0:12 offset1:14
	v_cvt_pk_bf16_f32 v118, v42, v43
	v_cvt_pk_bf16_f32 v119, v44, v45
	v_cvt_pk_bf16_f32 v120, v36, v37
	v_cvt_pk_bf16_f32 v121, v48, v49
	s_waitcnt lgkmcnt(0)
	s_nop 0
	v_mfma_f32_32x32x16_bf16 v[18:33], v[114:117], v[118:121], v[18:33]
	ds_read2_b64 v[112:115], v112 offset0:76 offset1:78
	s_waitcnt lgkmcnt(0)
	v_mfma_f32_32x32x16_bf16 v[2:17], v[112:115], v[118:121], v[2:17]
